# attention A loop: row-max as one dependent v_max3 chain instead of two interleaved chains
# baseline (speedup 1.0000x reference)
; #define FA_SB() __builtin_amdgcn_sched_barrier(0)
; __device__ __forceinline__ void attn_unit_a(FLAS unsigned char* lds, const Unit u) {
;     ...
;         FA_PVM(0); pC0[0] = fadd_s(pC0[0], off); pC1[0] = fadd_s(pC1[0], off); pC0[1] = fadd_s(pC0[1], off); pC1[1] = fadd_s(pC1[1], off); pC0[2] = fadd_s(pC0[2], off); pC1[2] = fadd_s(pC1[2], off); FA_SB();
;         FA_PVM(1); ra = __builtin_fmaxf(__builtin_fmaxf(pC0[0], pC0[1]), pC0[2]); rb = __builtin_fmaxf(__builtin_fmaxf(pC1[0], pC1[1]), pC1[2]); pC0[3] = fadd_s(pC0[3], off); pC1[3] = fadd_s(pC1[3], off); pC0[4] = fadd_s(pC0[4], off); pC1[4] = fadd_s(pC1[4], off); FA_SB();
;         FA_PVM(2); ra = __builtin_fmaxf(__builtin_fmaxf(ra, pC0[3]), pC0[4]); rb = __builtin_fmaxf(__builtin_fmaxf(rb, pC1[3]), pC1[4]); pC0[5] = fadd_s(pC0[5], off); pC1[5] = fadd_s(pC1[5], off); pC0[6] = fadd_s(pC0[6], off); pC1[6] = fadd_s(pC1[6], off); FA_SB();
;         FA_PVM(3); ra = __builtin_fmaxf(__builtin_fmaxf(ra, pC0[5]), pC0[6]); rb = __builtin_fmaxf(__builtin_fmaxf(rb, pC1[5]), pC1[6]); pC0[7] = fadd_s(pC0[7], off); pC1[7] = fadd_s(pC1[7], off); pC0[8] = fadd_s(pC0[8], off); pC1[8] = fadd_s(pC1[8], off); FA_SB();
;         FA_PVM(4); ra = __builtin_fmaxf(__builtin_fmaxf(ra, pC0[7]), pC0[8]); rb = __builtin_fmaxf(__builtin_fmaxf(rb, pC1[7]), pC1[8]); pC0[9] = fadd_s(pC0[9], off); pC1[9] = fadd_s(pC1[9], off); pC0[10] = fadd_s(pC0[10], off); pC1[10] = fadd_s(pC1[10], off); FA_SB();
;         FA_PVM(5); ra = __builtin_fmaxf(__builtin_fmaxf(ra, pC0[9]), pC0[10]); rb = __builtin_fmaxf(__builtin_fmaxf(rb, pC1[9]), pC1[10]); pC0[11] = fadd_s(pC0[11], off); pC1[11] = fadd_s(pC1[11], off); pC0[12] = fadd_s(pC0[12], off); pC1[12] = fadd_s(pC1[12], off); FA_SB();
;         FA_PVM(6); ra = __builtin_fmaxf(__builtin_fmaxf(ra, pC0[11]), pC0[12]); rb = __builtin_fmaxf(__builtin_fmaxf(rb, pC1[11]), pC1[12]); pC0[13] = fadd_s(pC0[13], off); pC1[13] = fadd_s(pC1[13], off); pC0[14] = fadd_s(pC0[14], off); pC1[14] = fadd_s(pC1[14], off); FA_SB();
;         FA_PVM(7); ra = __builtin_fmaxf(__builtin_fmaxf(ra, pC0[13]), pC0[14]); rb = __builtin_fmaxf(__builtin_fmaxf(rb, pC1[13]), pC1[14]); pC0[15] = fadd_s(pC0[15], off); pC1[15] = fadd_s(pC1[15], off); ra = __builtin_fmaxf(__builtin_fmaxf(ra, pC0[15]), pC1[15]); rm = __builtin_fmaxf(ra, rb); FA_SB();
;         rm = xhalf_max(rm);
;         FA_SB();
;         if (first || __any(rm > 8.0f)) {
.LBB0_437:
	v_max3_f32 v140, v96, v97, v98
	v_max3_f32 v140, v140, v99, v100
	v_cvt_pk_bf16_f32 v196, v72, v73
	v_cvt_pk_bf16_f32 v197, v74, v75
	v_add_f32_e32 v212, v80, v212
	v_add_f32_e32 v212, v81, v212
	v_mfma_f32_32x32x16_bf16 v[32:47], v[132:135], v[204:207], v[32:47]
	ds_read_b128 v[132:135], v200 offset:16416
	v_max3_f32 v140, v140, v101, v102
	v_max3_f32 v140, v140, v103, v104
	v_cvt_pk_bf16_f32 v198, v76, v77
	v_cvt_pk_bf16_f32 v199, v78, v79
	v_add_f32_e32 v212, v82, v212
	v_add_f32_e32 v212, v83, v212
	s_waitcnt lgkmcnt(1)
	v_mfma_f32_32x32x16_bf16 v[16:31], v[136:139], v[204:207], v[16:31]
	ds_read_b128 v[136:139], v200 offset:21024
	v_max3_f32 v140, v140, v105, v106
	v_max3_f32 v140, v140, v107, v108
	v_cvt_pk_bf16_f32 v192, v80, v81
	v_cvt_pk_bf16_f32 v193, v82, v83
	v_add_f32_e32 v212, v84, v212
	v_add_f32_e32 v212, v85, v212
	v_mfma_f32_32x32x16_bf16 v[0:15], v[128:131], v[204:207], v[0:15]
	ds_read_b128 v[128:131], v200 offset:25632
	v_max3_f32 v140, v140, v109, v110
	v_max3_f32 v140, v140, v111, v112
	v_cvt_pk_bf16_f32 v194, v84, v85
	v_cvt_pk_bf16_f32 v195, v86, v87
	v_add_f32_e32 v212, v86, v212
	v_add_f32_e32 v212, v87, v212
	s_waitcnt lgkmcnt(1)
	v_mfma_f32_32x32x16_bf16 v[48:63], v[132:135], v[196:199], v[48:63]
	ds_read_b128 v[132:135], v200 offset:30240
	v_max3_f32 v140, v140, v113, v114
	v_max3_f32 v140, v140, v115, v116
	v_cvt_pk_bf16_f32 v188, v88, v89
	v_cvt_pk_bf16_f32 v189, v90, v91
	v_add_f32_e32 v212, v88, v212
	v_add_f32_e32 v212, v89, v212
	v_mfma_f32_32x32x16_bf16 v[32:47], v[136:139], v[196:199], v[32:47]
	ds_read_b128 v[136:139], v200 offset:16448
	v_max3_f32 v140, v140, v117, v118
	v_max3_f32 v140, v140, v119, v120
	v_cvt_pk_bf16_f32 v190, v92, v93
	v_cvt_pk_bf16_f32 v191, v94, v95
	v_add_f32_e32 v212, v90, v212
	v_add_f32_e32 v212, v91, v212
	s_waitcnt lgkmcnt(1)
	v_mfma_f32_32x32x16_bf16 v[16:31], v[128:131], v[196:199], v[16:31]
	ds_read_b128 v[128:131], v200 offset:21056
	v_max3_f32 v140, v140, v121, v122
	v_max3_f32 v140, v140, v123, v124
	v_add_f32_e32 v212, v92, v212
	v_add_f32_e32 v212, v93, v212
	v_mfma_f32_32x32x16_bf16 v[0:15], v[132:135], v[196:199], v[0:15]
	ds_read_b128 v[132:135], v200 offset:25664
	v_max3_f32 v140, v140, v125, v126
	v_max_f32_e32 v140, v140, v127
	v_add_f32_e32 v212, v94, v212
	v_add_f32_e32 v212, v95, v212
	s_andn2_b64 vcc, exec, s[20:21]
	s_cbranch_vccnz .LBB0_440
	v_cmp_lt_f32_e32 vcc, s39, v140
	s_cbranch_vccnz .Lresc_e
	s_mov_b64 s[20:21], 0

; #define FA_SB() __builtin_amdgcn_sched_barrier(0)
; __device__ __forceinline__ void attn_unit_a(FLAS unsigned char* lds, const Unit u) {
;     ...
;         FA_PVM(0); pC0[0] = fadd_s(pC0[0], off); pC1[0] = fadd_s(pC1[0], off); pC0[1] = fadd_s(pC0[1], off); pC1[1] = fadd_s(pC1[1], off); pC0[2] = fadd_s(pC0[2], off); pC1[2] = fadd_s(pC1[2], off); FA_SB();
;         FA_PVM(1); ra = __builtin_fmaxf(__builtin_fmaxf(pC0[0], pC0[1]), pC0[2]); rb = __builtin_fmaxf(__builtin_fmaxf(pC1[0], pC1[1]), pC1[2]); pC0[3] = fadd_s(pC0[3], off); pC1[3] = fadd_s(pC1[3], off); pC0[4] = fadd_s(pC0[4], off); pC1[4] = fadd_s(pC1[4], off); FA_SB();
;         FA_PVM(2); ra = __builtin_fmaxf(__builtin_fmaxf(ra, pC0[3]), pC0[4]); rb = __builtin_fmaxf(__builtin_fmaxf(rb, pC1[3]), pC1[4]); pC0[5] = fadd_s(pC0[5], off); pC1[5] = fadd_s(pC1[5], off); pC0[6] = fadd_s(pC0[6], off); pC1[6] = fadd_s(pC1[6], off); FA_SB();
;         FA_PVM(3); ra = __builtin_fmaxf(__builtin_fmaxf(ra, pC0[5]), pC0[6]); rb = __builtin_fmaxf(__builtin_fmaxf(rb, pC1[5]), pC1[6]); pC0[7] = fadd_s(pC0[7], off); pC1[7] = fadd_s(pC1[7], off); pC0[8] = fadd_s(pC0[8], off); pC1[8] = fadd_s(pC1[8], off); FA_SB();
;         FA_PVM(4); ra = __builtin_fmaxf(__builtin_fmaxf(ra, pC0[7]), pC0[8]); rb = __builtin_fmaxf(__builtin_fmaxf(rb, pC1[7]), pC1[8]); pC0[9] = fadd_s(pC0[9], off); pC1[9] = fadd_s(pC1[9], off); pC0[10] = fadd_s(pC0[10], off); pC1[10] = fadd_s(pC1[10], off); FA_SB();
;         FA_PVM(5); ra = __builtin_fmaxf(__builtin_fmaxf(ra, pC0[9]), pC0[10]); rb = __builtin_fmaxf(__builtin_fmaxf(rb, pC1[9]), pC1[10]); pC0[11] = fadd_s(pC0[11], off); pC1[11] = fadd_s(pC1[11], off); pC0[12] = fadd_s(pC0[12], off); pC1[12] = fadd_s(pC1[12], off); FA_SB();
;         FA_PVM(6); ra = __builtin_fmaxf(__builtin_fmaxf(ra, pC0[11]), pC0[12]); rb = __builtin_fmaxf(__builtin_fmaxf(rb, pC1[11]), pC1[12]); pC0[13] = fadd_s(pC0[13], off); pC1[13] = fadd_s(pC1[13], off); pC0[14] = fadd_s(pC0[14], off); pC1[14] = fadd_s(pC1[14], off); FA_SB();
;         FA_PVM(7); ra = __builtin_fmaxf(__builtin_fmaxf(ra, pC0[13]), pC0[14]); rb = __builtin_fmaxf(__builtin_fmaxf(rb, pC1[13]), pC1[14]); pC0[15] = fadd_s(pC0[15], off); pC1[15] = fadd_s(pC1[15], off); ra = __builtin_fmaxf(__builtin_fmaxf(ra, pC0[15]), pC1[15]); rm = __builtin_fmaxf(ra, rb); FA_SB();
;         rm = xhalf_max(rm);
;         FA_SB();
;         if (first || __any(rm > 8.0f)) {
.LBB0_460:
	v_max3_f32 v96, v64, v65, v66
	v_max3_f32 v96, v96, v67, v68
	v_cvt_pk_bf16_f32 v232, v104, v105
	v_cvt_pk_bf16_f32 v233, v106, v107
	v_add_f32_e32 v212, v112, v212
	v_add_f32_e32 v212, v113, v212
	v_mfma_f32_32x32x16_bf16 v[32:47], v[132:135], v[140:143], v[32:47]
	ds_read_b128 v[132:135], v201 offset:16416
	v_max3_f32 v96, v96, v69, v70
	v_max3_f32 v96, v96, v71, v72
	v_cvt_pk_bf16_f32 v234, v108, v109
	v_cvt_pk_bf16_f32 v235, v110, v111
	v_add_f32_e32 v212, v114, v212
	v_add_f32_e32 v212, v115, v212
	s_waitcnt lgkmcnt(1)
	v_mfma_f32_32x32x16_bf16 v[16:31], v[136:139], v[140:143], v[16:31]
	ds_read_b128 v[136:139], v201 offset:21024
	v_max3_f32 v96, v96, v73, v74
	v_max3_f32 v96, v96, v75, v76
	v_add_f32_e32 v212, v116, v212
	v_add_f32_e32 v212, v117, v212
	v_mfma_f32_32x32x16_bf16 v[0:15], v[128:131], v[140:143], v[0:15]
	ds_read_b128 v[128:131], v201 offset:25632
	v_max3_f32 v96, v96, v77, v78
	v_max3_f32 v96, v96, v79, v80
	v_add_f32_e32 v212, v118, v212
	v_add_f32_e32 v212, v119, v212
	s_waitcnt lgkmcnt(1)
	v_mfma_f32_32x32x16_bf16 v[48:63], v[132:135], v[232:235], v[48:63]
	ds_read_b128 v[132:135], v201 offset:30240
	v_max3_f32 v96, v96, v81, v82
	v_max3_f32 v96, v96, v83, v84
	v_cvt_pk_bf16_f32 v140, v112, v113
	v_cvt_pk_bf16_f32 v141, v114, v115
	v_add_f32_e32 v212, v120, v212
	v_add_f32_e32 v212, v121, v212
	v_mfma_f32_32x32x16_bf16 v[32:47], v[136:139], v[232:235], v[32:47]
	ds_read_b128 v[136:139], v201 offset:16448
	v_max3_f32 v96, v96, v85, v86
	v_max3_f32 v96, v96, v87, v88
	v_cvt_pk_bf16_f32 v142, v116, v117
	v_cvt_pk_bf16_f32 v143, v118, v119
	v_add_f32_e32 v212, v122, v212
	v_add_f32_e32 v212, v123, v212
	s_waitcnt lgkmcnt(1)
	v_mfma_f32_32x32x16_bf16 v[16:31], v[128:131], v[232:235], v[16:31]
	ds_read_b128 v[128:131], v201 offset:21056
	v_max3_f32 v96, v96, v89, v90
	v_max3_f32 v96, v96, v91, v92
	v_add_f32_e32 v212, v124, v212
	v_add_f32_e32 v212, v125, v212
	v_mfma_f32_32x32x16_bf16 v[0:15], v[132:135], v[232:235], v[0:15]
	ds_read_b128 v[132:135], v201 offset:25664
	v_max3_f32 v96, v96, v93, v94
	v_max_f32_e32 v96, v96, v95
	v_add_f32_e32 v212, v126, v212
	v_add_f32_e32 v212, v127, v212
	v_cmp_lt_f32_e32 vcc, s39, v96
	s_mov_b64 s[0:1], 0
	s_cbranch_vccnz .Lresc_o
